# phase 1 (input modulation) hand-written: per-thread scale/shift hoisted, x rows through an 8-deep load ring instead of one row in flight
# speedup vs baseline: 1.0040x; 1.0040x over previous
; #define TIDX tid_fn()
; __device__ __forceinline__ void ph_modulate0(const Params& P) {
;   h16* A = (h16*)(P.ws + O_ABUF);
;   const size_t n4 = (size_t)NT * D / 4;
;   for (size_t i = (size_t)blockIdx.x * NTHR + TIDX; i < n4; i += (size_t)gridDim.x * NTHR) {
;     const size_t e = i * 4;
;     const int row = (int)(e / D), k = (int)(e % D);
;     const float* src = row < NL ? P.x + (size_t)row * D : P.ctx + (size_t)(row - NL) * D;
;     const float4 v = *(const float4*)(src + k);
;     const float* sh = mod_ptr(P, 0, row, 0) + k;
;     const float* sc = mod_ptr(P, 0, row, 1) + k;
;     h16x4 o;
;     o[0] = (h16)(v.x * (1.f + sc[0]) + sh[0]); o[1] = (h16)(v.y * (1.f + sc[1]) + sh[1]);
;     o[2] = (h16)(v.z * (1.f + sc[2]) + sh[2]); o[3] = (h16)(v.w * (1.f + sc[3]) + sh[3]);
;     *(h16x4*)(A + e) = o;
;   }
; }
.LBB0_256:
	s_or_b64 exec, exec, s[6:7]
	s_mov_b32 s3, 0
	s_mov_b64 s[4:5], s[96:97]
	s_lshl_b64 s[0:1], s[2:3], 9
	v_mov_b32_e32 v6, v0
	s_waitcnt lgkmcnt(0)
	s_barrier
	v_writelane_b32 v254, s0, 3
	v_ashrrev_i32_e32 v7, 31, v6
	s_nop 0
	v_writelane_b32 v254, s1, 4
	s_mov_b64 s[8:9], exec
	s_load_dwordx2 s[4:5], s[96:97], 0x0
	s_load_dwordx2 s[6:7], s[96:97], 0x10
	s_load_dwordx2 s[14:15], s[96:97], 0x178
	v_lshlrev_b32_e32 v1, 4, v0
	v_lshlrev_b32_e32 v2, 3, v0
	s_waitcnt lgkmcnt(0)
	s_add_u32 s16, s14, 0x4000
	s_addc_u32 s17, s15, 0
	s_add_u32 s18, s14, 0xbe4c000
	s_addc_u32 s19, s15, 0
	s_lshl_b32 s22, s2, 13
	s_add_u32 s10, s4, 0x0
	s_addc_u32 s11, s5, 0
	s_add_u32 s10, s10, s22
	s_addc_u32 s11, s11, 0
	s_lshl_b32 s22, s2, 12
	s_add_u32 s12, s18, 0x0
	s_addc_u32 s13, s19, 0
	s_add_u32 s12, s12, s22
	s_addc_u32 s13, s13, 0
	s_add_u32 s20, s16, 0x0
	s_addc_u32 s21, s17, 0
	global_load_dwordx4 v[8:11], v1, s[20:21]
	s_add_u32 s20, s20, 0x2000
	s_addc_u32 s21, s21, 0
	global_load_dwordx4 v[4:7], v1, s[20:21]
	global_load_dwordx4 v[32:35], v1, s[10:11]
	s_add_u32 s10, s10, 0x200000
	s_addc_u32 s11, s11, 0
	global_load_dwordx4 v[36:39], v1, s[10:11]
	s_add_u32 s10, s10, 0x200000
	s_addc_u32 s11, s11, 0
	global_load_dwordx4 v[40:43], v1, s[10:11]
	s_add_u32 s10, s10, 0x200000
	s_addc_u32 s11, s11, 0
	global_load_dwordx4 v[44:47], v1, s[10:11]
	s_add_u32 s10, s10, 0x200000
	s_addc_u32 s11, s11, 0
	global_load_dwordx4 v[48:51], v1, s[10:11]
	s_add_u32 s10, s10, 0x200000
	s_addc_u32 s11, s11, 0
	global_load_dwordx4 v[52:55], v1, s[10:11]
	s_add_u32 s10, s10, 0x200000
	s_addc_u32 s11, s11, 0
	global_load_dwordx4 v[56:59], v1, s[10:11]
	s_add_u32 s10, s10, 0x200000
	s_addc_u32 s11, s11, 0
	global_load_dwordx4 v[60:63], v1, s[10:11]
	s_add_u32 s10, s10, 0x200000
	s_addc_u32 s11, s11, 0
	s_waitcnt vmcnt(8)
	v_pk_add_f32 v[4:5], v[4:5], 1.0 op_sel_hi:[1,0]
	v_pk_add_f32 v[6:7], v[6:7], 1.0 op_sel_hi:[1,0]
	s_waitcnt vmcnt(7)
	v_pk_fma_f32 v[32:33], v[32:33], v[4:5], v[8:9]
	v_pk_fma_f32 v[34:35], v[34:35], v[6:7], v[10:11]
	v_cvt_pk_f16_f32 v12, v32, v33
	v_cvt_pk_f16_f32 v13, v34, v35
	global_store_dwordx2 v2, v[12:13], s[12:13]
	s_add_u32 s12, s12, 0x100000
	s_addc_u32 s13, s13, 0
	global_load_dwordx4 v[32:35], v1, s[10:11]
	s_add_u32 s10, s10, 0x200000
	s_addc_u32 s11, s11, 0
	s_waitcnt vmcnt(8)
	v_pk_fma_f32 v[36:37], v[36:37], v[4:5], v[8:9]
	v_pk_fma_f32 v[38:39], v[38:39], v[6:7], v[10:11]
	v_cvt_pk_f16_f32 v14, v36, v37
	v_cvt_pk_f16_f32 v15, v38, v39
	global_store_dwordx2 v2, v[14:15], s[12:13]
	s_add_u32 s12, s12, 0x100000
	s_addc_u32 s13, s13, 0
	global_load_dwordx4 v[36:39], v1, s[10:11]
	s_add_u32 s10, s10, 0x200000
	s_addc_u32 s11, s11, 0
	s_waitcnt vmcnt(9)
	v_pk_fma_f32 v[40:41], v[40:41], v[4:5], v[8:9]
	v_pk_fma_f32 v[42:43], v[42:43], v[6:7], v[10:11]
	v_cvt_pk_f16_f32 v16, v40, v41
	v_cvt_pk_f16_f32 v17, v42, v43
	global_store_dwordx2 v2, v[16:17], s[12:13]
	s_add_u32 s12, s12, 0x100000
	s_addc_u32 s13, s13, 0
	global_load_dwordx4 v[40:43], v1, s[10:11]
	s_add_u32 s10, s10, 0x200000
	s_addc_u32 s11, s11, 0
	s_waitcnt vmcnt(10)
	v_pk_fma_f32 v[44:45], v[44:45], v[4:5], v[8:9]
	v_pk_fma_f32 v[46:47], v[46:47], v[6:7], v[10:11]
	v_cvt_pk_f16_f32 v18, v44, v45
	v_cvt_pk_f16_f32 v19, v46, v47
	global_store_dwordx2 v2, v[18:19], s[12:13]
	s_add_u32 s12, s12, 0x100000
	s_addc_u32 s13, s13, 0
	global_load_dwordx4 v[44:47], v1, s[10:11]
	s_add_u32 s10, s10, 0x200000
	s_addc_u32 s11, s11, 0
	s_waitcnt vmcnt(11)
	v_pk_fma_f32 v[48:49], v[48:49], v[4:5], v[8:9]
	v_pk_fma_f32 v[50:51], v[50:51], v[6:7], v[10:11]
	v_cvt_pk_f16_f32 v12, v48, v49
	v_cvt_pk_f16_f32 v13, v50, v51
	global_store_dwordx2 v2, v[12:13], s[12:13]
	s_add_u32 s12, s12, 0x100000
	s_addc_u32 s13, s13, 0
	global_load_dwordx4 v[48:51], v1, s[10:11]
	s_add_u32 s10, s10, 0x200000
	s_addc_u32 s11, s11, 0
	s_waitcnt vmcnt(12)
	v_pk_fma_f32 v[52:53], v[52:53], v[4:5], v[8:9]
	v_pk_fma_f32 v[54:55], v[54:55], v[6:7], v[10:11]
	v_cvt_pk_f16_f32 v14, v52, v53
	v_cvt_pk_f16_f32 v15, v54, v55
	global_store_dwordx2 v2, v[14:15], s[12:13]
	s_add_u32 s12, s12, 0x100000
	s_addc_u32 s13, s13, 0
	global_load_dwordx4 v[52:55], v1, s[10:11]
	s_add_u32 s10, s10, 0x200000
	s_addc_u32 s11, s11, 0
	s_waitcnt vmcnt(13)
	v_pk_fma_f32 v[56:57], v[56:57], v[4:5], v[8:9]
	v_pk_fma_f32 v[58:59], v[58:59], v[6:7], v[10:11]
	v_cvt_pk_f16_f32 v16, v56, v57
	v_cvt_pk_f16_f32 v17, v58, v59
	global_store_dwordx2 v2, v[16:17], s[12:13]
	s_add_u32 s12, s12, 0x100000
	s_addc_u32 s13, s13, 0
	global_load_dwordx4 v[56:59], v1, s[10:11]
	s_add_u32 s10, s10, 0x200000
	s_addc_u32 s11, s11, 0
	s_waitcnt vmcnt(14)
	v_pk_fma_f32 v[60:61], v[60:61], v[4:5], v[8:9]
	v_pk_fma_f32 v[62:63], v[62:63], v[6:7], v[10:11]
	v_cvt_pk_f16_f32 v18, v60, v61
	v_cvt_pk_f16_f32 v19, v62, v63
	global_store_dwordx2 v2, v[18:19], s[12:13]
	s_add_u32 s12, s12, 0x100000
	s_addc_u32 s13, s13, 0
	global_load_dwordx4 v[60:63], v1, s[10:11]
	s_add_u32 s10, s10, 0x200000
	s_addc_u32 s11, s11, 0
	s_mov_b32 s23, 6
; #define TIDX tid_fn()
; __device__ __forceinline__ void ph_modulate0(const Params& P) {
;     ...
;   for (size_t i = (size_t)blockIdx.x * NTHR + TIDX; i < n4; i += (size_t)gridDim.x * NTHR) {
;     const size_t e = i * 4;
;     const int row = (int)(e / D), k = (int)(e % D);
;     const float* src = row < NL ? P.x + (size_t)row * D : P.ctx + (size_t)(row - NL) * D;
;     const float4 v = *(const float4*)(src + k);
;     const float* sh = mod_ptr(P, 0, row, 0) + k;
;     const float* sc = mod_ptr(P, 0, row, 1) + k;
;     h16x4 o;
;     o[0] = (h16)(v.x * (1.f + sc[0]) + sh[0]); o[1] = (h16)(v.y * (1.f + sc[1]) + sh[1]);
;     o[2] = (h16)(v.z * (1.f + sc[2]) + sh[2]); o[3] = (h16)(v.w * (1.f + sc[3]) + sh[3]);
;     *(h16x4*)(A + e) = o;
;   }
.Lmod0_loop0:
	s_waitcnt vmcnt(14)
	v_pk_fma_f32 v[32:33], v[32:33], v[4:5], v[8:9]
	v_pk_fma_f32 v[34:35], v[34:35], v[6:7], v[10:11]
	v_cvt_pk_f16_f32 v12, v32, v33
	v_cvt_pk_f16_f32 v13, v34, v35
	global_store_dwordx2 v2, v[12:13], s[12:13]
	s_add_u32 s12, s12, 0x100000
	s_addc_u32 s13, s13, 0
	global_load_dwordx4 v[32:35], v1, s[10:11]
	s_add_u32 s10, s10, 0x200000
	s_addc_u32 s11, s11, 0
	s_waitcnt vmcnt(14)
	v_pk_fma_f32 v[36:37], v[36:37], v[4:5], v[8:9]
	v_pk_fma_f32 v[38:39], v[38:39], v[6:7], v[10:11]
	v_cvt_pk_f16_f32 v14, v36, v37
	v_cvt_pk_f16_f32 v15, v38, v39
	global_store_dwordx2 v2, v[14:15], s[12:13]
	s_add_u32 s12, s12, 0x100000
	s_addc_u32 s13, s13, 0
	global_load_dwordx4 v[36:39], v1, s[10:11]
	s_add_u32 s10, s10, 0x200000
	s_addc_u32 s11, s11, 0
	s_waitcnt vmcnt(14)
	v_pk_fma_f32 v[40:41], v[40:41], v[4:5], v[8:9]
	v_pk_fma_f32 v[42:43], v[42:43], v[6:7], v[10:11]
	v_cvt_pk_f16_f32 v16, v40, v41
	v_cvt_pk_f16_f32 v17, v42, v43
	global_store_dwordx2 v2, v[16:17], s[12:13]
	s_add_u32 s12, s12, 0x100000
	s_addc_u32 s13, s13, 0
	global_load_dwordx4 v[40:43], v1, s[10:11]
	s_add_u32 s10, s10, 0x200000
	s_addc_u32 s11, s11, 0
	s_waitcnt vmcnt(14)
	v_pk_fma_f32 v[44:45], v[44:45], v[4:5], v[8:9]
	v_pk_fma_f32 v[46:47], v[46:47], v[6:7], v[10:11]
	v_cvt_pk_f16_f32 v18, v44, v45
	v_cvt_pk_f16_f32 v19, v46, v47
	global_store_dwordx2 v2, v[18:19], s[12:13]
	s_add_u32 s12, s12, 0x100000
	s_addc_u32 s13, s13, 0
	global_load_dwordx4 v[44:47], v1, s[10:11]
	s_add_u32 s10, s10, 0x200000
	s_addc_u32 s11, s11, 0
	s_waitcnt vmcnt(14)
	v_pk_fma_f32 v[48:49], v[48:49], v[4:5], v[8:9]
	v_pk_fma_f32 v[50:51], v[50:51], v[6:7], v[10:11]
	v_cvt_pk_f16_f32 v12, v48, v49
	v_cvt_pk_f16_f32 v13, v50, v51
	global_store_dwordx2 v2, v[12:13], s[12:13]
	s_add_u32 s12, s12, 0x100000
	s_addc_u32 s13, s13, 0
	global_load_dwordx4 v[48:51], v1, s[10:11]
	s_add_u32 s10, s10, 0x200000
	s_addc_u32 s11, s11, 0
	s_waitcnt vmcnt(14)
	v_pk_fma_f32 v[52:53], v[52:53], v[4:5], v[8:9]
	v_pk_fma_f32 v[54:55], v[54:55], v[6:7], v[10:11]
	v_cvt_pk_f16_f32 v14, v52, v53
	v_cvt_pk_f16_f32 v15, v54, v55
	global_store_dwordx2 v2, v[14:15], s[12:13]
	s_add_u32 s12, s12, 0x100000
	s_addc_u32 s13, s13, 0
	global_load_dwordx4 v[52:55], v1, s[10:11]
	s_add_u32 s10, s10, 0x200000
	s_addc_u32 s11, s11, 0
	s_waitcnt vmcnt(14)
	v_pk_fma_f32 v[56:57], v[56:57], v[4:5], v[8:9]
	v_pk_fma_f32 v[58:59], v[58:59], v[6:7], v[10:11]
	v_cvt_pk_f16_f32 v16, v56, v57
	v_cvt_pk_f16_f32 v17, v58, v59
	global_store_dwordx2 v2, v[16:17], s[12:13]
	s_add_u32 s12, s12, 0x100000
	s_addc_u32 s13, s13, 0
	global_load_dwordx4 v[56:59], v1, s[10:11]
	s_add_u32 s10, s10, 0x200000
	s_addc_u32 s11, s11, 0
	s_waitcnt vmcnt(14)
	v_pk_fma_f32 v[60:61], v[60:61], v[4:5], v[8:9]
	v_pk_fma_f32 v[62:63], v[62:63], v[6:7], v[10:11]
	v_cvt_pk_f16_f32 v18, v60, v61
	v_cvt_pk_f16_f32 v19, v62, v63
	global_store_dwordx2 v2, v[18:19], s[12:13]
	s_add_u32 s12, s12, 0x100000
	s_addc_u32 s13, s13, 0
	global_load_dwordx4 v[60:63], v1, s[10:11]
	s_add_u32 s10, s10, 0x200000
	s_addc_u32 s11, s11, 0
	s_sub_u32 s23, s23, 1
	s_cmp_lg_u32 s23, 0
	s_cbranch_scc1 .Lmod0_loop0
	s_waitcnt vmcnt(0)
	v_pk_fma_f32 v[32:33], v[32:33], v[4:5], v[8:9]
	v_pk_fma_f32 v[34:35], v[34:35], v[6:7], v[10:11]
	v_cvt_pk_f16_f32 v12, v32, v33
	v_cvt_pk_f16_f32 v13, v34, v35
	global_store_dwordx2 v2, v[12:13], s[12:13]
	s_add_u32 s12, s12, 0x100000
	s_addc_u32 s13, s13, 0
	v_pk_fma_f32 v[36:37], v[36:37], v[4:5], v[8:9]
	v_pk_fma_f32 v[38:39], v[38:39], v[6:7], v[10:11]
	v_cvt_pk_f16_f32 v14, v36, v37
	v_cvt_pk_f16_f32 v15, v38, v39
	global_store_dwordx2 v2, v[14:15], s[12:13]
	s_add_u32 s12, s12, 0x100000
	s_addc_u32 s13, s13, 0
	v_pk_fma_f32 v[40:41], v[40:41], v[4:5], v[8:9]
	v_pk_fma_f32 v[42:43], v[42:43], v[6:7], v[10:11]
	v_cvt_pk_f16_f32 v16, v40, v41
	v_cvt_pk_f16_f32 v17, v42, v43
	global_store_dwordx2 v2, v[16:17], s[12:13]
	s_add_u32 s12, s12, 0x100000
	s_addc_u32 s13, s13, 0
	v_pk_fma_f32 v[44:45], v[44:45], v[4:5], v[8:9]
	v_pk_fma_f32 v[46:47], v[46:47], v[6:7], v[10:11]
	v_cvt_pk_f16_f32 v18, v44, v45
	v_cvt_pk_f16_f32 v19, v46, v47
	global_store_dwordx2 v2, v[18:19], s[12:13]
	s_add_u32 s12, s12, 0x100000
	s_addc_u32 s13, s13, 0
	v_pk_fma_f32 v[48:49], v[48:49], v[4:5], v[8:9]
	v_pk_fma_f32 v[50:51], v[50:51], v[6:7], v[10:11]
	v_cvt_pk_f16_f32 v12, v48, v49
	v_cvt_pk_f16_f32 v13, v50, v51
	global_store_dwordx2 v2, v[12:13], s[12:13]
	s_add_u32 s12, s12, 0x100000
	s_addc_u32 s13, s13, 0
	v_pk_fma_f32 v[52:53], v[52:53], v[4:5], v[8:9]
	v_pk_fma_f32 v[54:55], v[54:55], v[6:7], v[10:11]
	v_cvt_pk_f16_f32 v14, v52, v53
	v_cvt_pk_f16_f32 v15, v54, v55
	global_store_dwordx2 v2, v[14:15], s[12:13]
	s_add_u32 s12, s12, 0x100000
	s_addc_u32 s13, s13, 0
	v_pk_fma_f32 v[56:57], v[56:57], v[4:5], v[8:9]
	v_pk_fma_f32 v[58:59], v[58:59], v[6:7], v[10:11]
	v_cvt_pk_f16_f32 v16, v56, v57
	v_cvt_pk_f16_f32 v17, v58, v59
	global_store_dwordx2 v2, v[16:17], s[12:13]
	s_add_u32 s12, s12, 0x100000
	s_addc_u32 s13, s13, 0
	v_pk_fma_f32 v[60:61], v[60:61], v[4:5], v[8:9]
	v_pk_fma_f32 v[62:63], v[62:63], v[6:7], v[10:11]
	v_cvt_pk_f16_f32 v18, v60, v61
	v_cvt_pk_f16_f32 v19, v62, v63
	global_store_dwordx2 v2, v[18:19], s[12:13]
	s_add_u32 s12, s12, 0x100000
	s_addc_u32 s13, s13, 0
	s_lshl_b32 s22, s2, 13
	s_add_u32 s10, s4, 0x8000000
	s_addc_u32 s11, s5, 0
	s_add_u32 s10, s10, s22
	s_addc_u32 s11, s11, 0
	s_lshl_b32 s22, s2, 12
	s_add_u32 s12, s18, 0x4000000
	s_addc_u32 s13, s19, 0
	s_add_u32 s12, s12, s22
	s_addc_u32 s13, s13, 0
	s_add_u32 s20, s16, 0xc000
	s_addc_u32 s21, s17, 0
	global_load_dwordx4 v[8:11], v1, s[20:21]
	s_add_u32 s20, s20, 0x2000
	s_addc_u32 s21, s21, 0
	global_load_dwordx4 v[4:7], v1, s[20:21]
	global_load_dwordx4 v[32:35], v1, s[10:11]
	s_add_u32 s10, s10, 0x200000
	s_addc_u32 s11, s11, 0
	global_load_dwordx4 v[36:39], v1, s[10:11]
	s_add_u32 s10, s10, 0x200000
	s_addc_u32 s11, s11, 0
	global_load_dwordx4 v[40:43], v1, s[10:11]
	s_add_u32 s10, s10, 0x200000
	s_addc_u32 s11, s11, 0
	global_load_dwordx4 v[44:47], v1, s[10:11]
	s_add_u32 s10, s10, 0x200000
	s_addc_u32 s11, s11, 0
	global_load_dwordx4 v[48:51], v1, s[10:11]
	s_add_u32 s10, s10, 0x200000
	s_addc_u32 s11, s11, 0
	global_load_dwordx4 v[52:55], v1, s[10:11]
	s_add_u32 s10, s10, 0x200000
	s_addc_u32 s11, s11, 0
	global_load_dwordx4 v[56:59], v1, s[10:11]
	s_add_u32 s10, s10, 0x200000
	s_addc_u32 s11, s11, 0
	global_load_dwordx4 v[60:63], v1, s[10:11]
	s_add_u32 s10, s10, 0x200000
	s_addc_u32 s11, s11, 0
	s_waitcnt vmcnt(8)
; #define TIDX tid_fn()
; __device__ __forceinline__ void ph_modulate0(const Params& P) {
;     ...
;   for (size_t i = (size_t)blockIdx.x * NTHR + TIDX; i < n4; i += (size_t)gridDim.x * NTHR) {
;     const size_t e = i * 4;
;     const int row = (int)(e / D), k = (int)(e % D);
;     const float* src = row < NL ? P.x + (size_t)row * D : P.ctx + (size_t)(row - NL) * D;
;     const float4 v = *(const float4*)(src + k);
;     const float* sh = mod_ptr(P, 0, row, 0) + k;
;     const float* sc = mod_ptr(P, 0, row, 1) + k;
;     h16x4 o;
;     o[0] = (h16)(v.x * (1.f + sc[0]) + sh[0]); o[1] = (h16)(v.y * (1.f + sc[1]) + sh[1]);
;     o[2] = (h16)(v.z * (1.f + sc[2]) + sh[2]); o[3] = (h16)(v.w * (1.f + sc[3]) + sh[3]);
;     *(h16x4*)(A + e) = o;
;   }
	v_pk_add_f32 v[4:5], v[4:5], 1.0 op_sel_hi:[1,0]
	v_pk_add_f32 v[6:7], v[6:7], 1.0 op_sel_hi:[1,0]
	s_waitcnt vmcnt(7)
	v_pk_fma_f32 v[32:33], v[32:33], v[4:5], v[8:9]
	v_pk_fma_f32 v[34:35], v[34:35], v[6:7], v[10:11]
	v_cvt_pk_f16_f32 v12, v32, v33
	v_cvt_pk_f16_f32 v13, v34, v35
	global_store_dwordx2 v2, v[12:13], s[12:13]
	s_add_u32 s12, s12, 0x100000
	s_addc_u32 s13, s13, 0
	global_load_dwordx4 v[32:35], v1, s[10:11]
	s_add_u32 s10, s10, 0x200000
	s_addc_u32 s11, s11, 0
	s_waitcnt vmcnt(8)
	v_pk_fma_f32 v[36:37], v[36:37], v[4:5], v[8:9]
	v_pk_fma_f32 v[38:39], v[38:39], v[6:7], v[10:11]
	v_cvt_pk_f16_f32 v14, v36, v37
	v_cvt_pk_f16_f32 v15, v38, v39
	global_store_dwordx2 v2, v[14:15], s[12:13]
	s_add_u32 s12, s12, 0x100000
	s_addc_u32 s13, s13, 0
	global_load_dwordx4 v[36:39], v1, s[10:11]
	s_add_u32 s10, s10, 0x200000
	s_addc_u32 s11, s11, 0
	s_waitcnt vmcnt(9)
	v_pk_fma_f32 v[40:41], v[40:41], v[4:5], v[8:9]
	v_pk_fma_f32 v[42:43], v[42:43], v[6:7], v[10:11]
	v_cvt_pk_f16_f32 v16, v40, v41
	v_cvt_pk_f16_f32 v17, v42, v43
	global_store_dwordx2 v2, v[16:17], s[12:13]
	s_add_u32 s12, s12, 0x100000
	s_addc_u32 s13, s13, 0
	global_load_dwordx4 v[40:43], v1, s[10:11]
	s_add_u32 s10, s10, 0x200000
	s_addc_u32 s11, s11, 0
	s_waitcnt vmcnt(10)
	v_pk_fma_f32 v[44:45], v[44:45], v[4:5], v[8:9]
	v_pk_fma_f32 v[46:47], v[46:47], v[6:7], v[10:11]
	v_cvt_pk_f16_f32 v18, v44, v45
	v_cvt_pk_f16_f32 v19, v46, v47
	global_store_dwordx2 v2, v[18:19], s[12:13]
	s_add_u32 s12, s12, 0x100000
	s_addc_u32 s13, s13, 0
	global_load_dwordx4 v[44:47], v1, s[10:11]
	s_add_u32 s10, s10, 0x200000
	s_addc_u32 s11, s11, 0
	s_waitcnt vmcnt(11)
	v_pk_fma_f32 v[48:49], v[48:49], v[4:5], v[8:9]
	v_pk_fma_f32 v[50:51], v[50:51], v[6:7], v[10:11]
	v_cvt_pk_f16_f32 v12, v48, v49
	v_cvt_pk_f16_f32 v13, v50, v51
	global_store_dwordx2 v2, v[12:13], s[12:13]
	s_add_u32 s12, s12, 0x100000
	s_addc_u32 s13, s13, 0
	global_load_dwordx4 v[48:51], v1, s[10:11]
	s_add_u32 s10, s10, 0x200000
	s_addc_u32 s11, s11, 0
	s_waitcnt vmcnt(12)
	v_pk_fma_f32 v[52:53], v[52:53], v[4:5], v[8:9]
	v_pk_fma_f32 v[54:55], v[54:55], v[6:7], v[10:11]
	v_cvt_pk_f16_f32 v14, v52, v53
	v_cvt_pk_f16_f32 v15, v54, v55
	global_store_dwordx2 v2, v[14:15], s[12:13]
	s_add_u32 s12, s12, 0x100000
	s_addc_u32 s13, s13, 0
	global_load_dwordx4 v[52:55], v1, s[10:11]
	s_add_u32 s10, s10, 0x200000
	s_addc_u32 s11, s11, 0
	s_waitcnt vmcnt(13)
	v_pk_fma_f32 v[56:57], v[56:57], v[4:5], v[8:9]
	v_pk_fma_f32 v[58:59], v[58:59], v[6:7], v[10:11]
	v_cvt_pk_f16_f32 v16, v56, v57
	v_cvt_pk_f16_f32 v17, v58, v59
	global_store_dwordx2 v2, v[16:17], s[12:13]
	s_add_u32 s12, s12, 0x100000
	s_addc_u32 s13, s13, 0
	global_load_dwordx4 v[56:59], v1, s[10:11]
	s_add_u32 s10, s10, 0x200000
	s_addc_u32 s11, s11, 0
	s_waitcnt vmcnt(14)
	v_pk_fma_f32 v[60:61], v[60:61], v[4:5], v[8:9]
	v_pk_fma_f32 v[62:63], v[62:63], v[6:7], v[10:11]
	v_cvt_pk_f16_f32 v18, v60, v61
	v_cvt_pk_f16_f32 v19, v62, v63
	global_store_dwordx2 v2, v[18:19], s[12:13]
	s_add_u32 s12, s12, 0x100000
	s_addc_u32 s13, s13, 0
	global_load_dwordx4 v[60:63], v1, s[10:11]
	s_add_u32 s10, s10, 0x200000
	s_addc_u32 s11, s11, 0
	s_mov_b32 s23, 6
; #define TIDX tid_fn()
; __device__ __forceinline__ void ph_modulate0(const Params& P) {
;     ...
;   for (size_t i = (size_t)blockIdx.x * NTHR + TIDX; i < n4; i += (size_t)gridDim.x * NTHR) {
;     const size_t e = i * 4;
;     const int row = (int)(e / D), k = (int)(e % D);
;     const float* src = row < NL ? P.x + (size_t)row * D : P.ctx + (size_t)(row - NL) * D;
;     const float4 v = *(const float4*)(src + k);
;     const float* sh = mod_ptr(P, 0, row, 0) + k;
;     const float* sc = mod_ptr(P, 0, row, 1) + k;
;     h16x4 o;
;     o[0] = (h16)(v.x * (1.f + sc[0]) + sh[0]); o[1] = (h16)(v.y * (1.f + sc[1]) + sh[1]);
;     o[2] = (h16)(v.z * (1.f + sc[2]) + sh[2]); o[3] = (h16)(v.w * (1.f + sc[3]) + sh[3]);
;     *(h16x4*)(A + e) = o;
;   }
.Lmod0_loop1:
	s_waitcnt vmcnt(14)
	v_pk_fma_f32 v[32:33], v[32:33], v[4:5], v[8:9]
	v_pk_fma_f32 v[34:35], v[34:35], v[6:7], v[10:11]
	v_cvt_pk_f16_f32 v12, v32, v33
	v_cvt_pk_f16_f32 v13, v34, v35
	global_store_dwordx2 v2, v[12:13], s[12:13]
	s_add_u32 s12, s12, 0x100000
	s_addc_u32 s13, s13, 0
	global_load_dwordx4 v[32:35], v1, s[10:11]
	s_add_u32 s10, s10, 0x200000
	s_addc_u32 s11, s11, 0
	s_waitcnt vmcnt(14)
	v_pk_fma_f32 v[36:37], v[36:37], v[4:5], v[8:9]
	v_pk_fma_f32 v[38:39], v[38:39], v[6:7], v[10:11]
	v_cvt_pk_f16_f32 v14, v36, v37
	v_cvt_pk_f16_f32 v15, v38, v39
	global_store_dwordx2 v2, v[14:15], s[12:13]
	s_add_u32 s12, s12, 0x100000
	s_addc_u32 s13, s13, 0
	global_load_dwordx4 v[36:39], v1, s[10:11]
	s_add_u32 s10, s10, 0x200000
	s_addc_u32 s11, s11, 0
	s_waitcnt vmcnt(14)
	v_pk_fma_f32 v[40:41], v[40:41], v[4:5], v[8:9]
	v_pk_fma_f32 v[42:43], v[42:43], v[6:7], v[10:11]
	v_cvt_pk_f16_f32 v16, v40, v41
	v_cvt_pk_f16_f32 v17, v42, v43
	global_store_dwordx2 v2, v[16:17], s[12:13]
	s_add_u32 s12, s12, 0x100000
	s_addc_u32 s13, s13, 0
	global_load_dwordx4 v[40:43], v1, s[10:11]
	s_add_u32 s10, s10, 0x200000
	s_addc_u32 s11, s11, 0
	s_waitcnt vmcnt(14)
	v_pk_fma_f32 v[44:45], v[44:45], v[4:5], v[8:9]
	v_pk_fma_f32 v[46:47], v[46:47], v[6:7], v[10:11]
	v_cvt_pk_f16_f32 v18, v44, v45
	v_cvt_pk_f16_f32 v19, v46, v47
	global_store_dwordx2 v2, v[18:19], s[12:13]
	s_add_u32 s12, s12, 0x100000
	s_addc_u32 s13, s13, 0
	global_load_dwordx4 v[44:47], v1, s[10:11]
	s_add_u32 s10, s10, 0x200000
	s_addc_u32 s11, s11, 0
	s_waitcnt vmcnt(14)
	v_pk_fma_f32 v[48:49], v[48:49], v[4:5], v[8:9]
	v_pk_fma_f32 v[50:51], v[50:51], v[6:7], v[10:11]
	v_cvt_pk_f16_f32 v12, v48, v49
	v_cvt_pk_f16_f32 v13, v50, v51
	global_store_dwordx2 v2, v[12:13], s[12:13]
	s_add_u32 s12, s12, 0x100000
	s_addc_u32 s13, s13, 0
	global_load_dwordx4 v[48:51], v1, s[10:11]
	s_add_u32 s10, s10, 0x200000
	s_addc_u32 s11, s11, 0
	s_waitcnt vmcnt(14)
	v_pk_fma_f32 v[52:53], v[52:53], v[4:5], v[8:9]
	v_pk_fma_f32 v[54:55], v[54:55], v[6:7], v[10:11]
	v_cvt_pk_f16_f32 v14, v52, v53
	v_cvt_pk_f16_f32 v15, v54, v55
	global_store_dwordx2 v2, v[14:15], s[12:13]
	s_add_u32 s12, s12, 0x100000
	s_addc_u32 s13, s13, 0
	global_load_dwordx4 v[52:55], v1, s[10:11]
	s_add_u32 s10, s10, 0x200000
	s_addc_u32 s11, s11, 0
	s_waitcnt vmcnt(14)
	v_pk_fma_f32 v[56:57], v[56:57], v[4:5], v[8:9]
	v_pk_fma_f32 v[58:59], v[58:59], v[6:7], v[10:11]
	v_cvt_pk_f16_f32 v16, v56, v57
	v_cvt_pk_f16_f32 v17, v58, v59
	global_store_dwordx2 v2, v[16:17], s[12:13]
	s_add_u32 s12, s12, 0x100000
	s_addc_u32 s13, s13, 0
	global_load_dwordx4 v[56:59], v1, s[10:11]
	s_add_u32 s10, s10, 0x200000
	s_addc_u32 s11, s11, 0
	s_waitcnt vmcnt(14)
	v_pk_fma_f32 v[60:61], v[60:61], v[4:5], v[8:9]
	v_pk_fma_f32 v[62:63], v[62:63], v[6:7], v[10:11]
	v_cvt_pk_f16_f32 v18, v60, v61
	v_cvt_pk_f16_f32 v19, v62, v63
	global_store_dwordx2 v2, v[18:19], s[12:13]
	s_add_u32 s12, s12, 0x100000
	s_addc_u32 s13, s13, 0
	global_load_dwordx4 v[60:63], v1, s[10:11]
	s_add_u32 s10, s10, 0x200000
	s_addc_u32 s11, s11, 0
	s_sub_u32 s23, s23, 1
	s_cmp_lg_u32 s23, 0
	s_cbranch_scc1 .Lmod0_loop1
	s_waitcnt vmcnt(0)
	v_pk_fma_f32 v[32:33], v[32:33], v[4:5], v[8:9]
	v_pk_fma_f32 v[34:35], v[34:35], v[6:7], v[10:11]
	v_cvt_pk_f16_f32 v12, v32, v33
	v_cvt_pk_f16_f32 v13, v34, v35
	global_store_dwordx2 v2, v[12:13], s[12:13]
	s_add_u32 s12, s12, 0x100000
	s_addc_u32 s13, s13, 0
	v_pk_fma_f32 v[36:37], v[36:37], v[4:5], v[8:9]
	v_pk_fma_f32 v[38:39], v[38:39], v[6:7], v[10:11]
	v_cvt_pk_f16_f32 v14, v36, v37
	v_cvt_pk_f16_f32 v15, v38, v39
	global_store_dwordx2 v2, v[14:15], s[12:13]
	s_add_u32 s12, s12, 0x100000
	s_addc_u32 s13, s13, 0
	v_pk_fma_f32 v[40:41], v[40:41], v[4:5], v[8:9]
	v_pk_fma_f32 v[42:43], v[42:43], v[6:7], v[10:11]
	v_cvt_pk_f16_f32 v16, v40, v41
	v_cvt_pk_f16_f32 v17, v42, v43
	global_store_dwordx2 v2, v[16:17], s[12:13]
	s_add_u32 s12, s12, 0x100000
	s_addc_u32 s13, s13, 0
	v_pk_fma_f32 v[44:45], v[44:45], v[4:5], v[8:9]
	v_pk_fma_f32 v[46:47], v[46:47], v[6:7], v[10:11]
	v_cvt_pk_f16_f32 v18, v44, v45
	v_cvt_pk_f16_f32 v19, v46, v47
	global_store_dwordx2 v2, v[18:19], s[12:13]
	s_add_u32 s12, s12, 0x100000
	s_addc_u32 s13, s13, 0
	v_pk_fma_f32 v[48:49], v[48:49], v[4:5], v[8:9]
	v_pk_fma_f32 v[50:51], v[50:51], v[6:7], v[10:11]
	v_cvt_pk_f16_f32 v12, v48, v49
	v_cvt_pk_f16_f32 v13, v50, v51
	global_store_dwordx2 v2, v[12:13], s[12:13]
	s_add_u32 s12, s12, 0x100000
	s_addc_u32 s13, s13, 0
	v_pk_fma_f32 v[52:53], v[52:53], v[4:5], v[8:9]
	v_pk_fma_f32 v[54:55], v[54:55], v[6:7], v[10:11]
	v_cvt_pk_f16_f32 v14, v52, v53
	v_cvt_pk_f16_f32 v15, v54, v55
	global_store_dwordx2 v2, v[14:15], s[12:13]
	s_add_u32 s12, s12, 0x100000
	s_addc_u32 s13, s13, 0
	v_pk_fma_f32 v[56:57], v[56:57], v[4:5], v[8:9]
	v_pk_fma_f32 v[58:59], v[58:59], v[6:7], v[10:11]
	v_cvt_pk_f16_f32 v16, v56, v57
	v_cvt_pk_f16_f32 v17, v58, v59
	global_store_dwordx2 v2, v[16:17], s[12:13]
	s_add_u32 s12, s12, 0x100000
	s_addc_u32 s13, s13, 0
	v_pk_fma_f32 v[60:61], v[60:61], v[4:5], v[8:9]
	v_pk_fma_f32 v[62:63], v[62:63], v[6:7], v[10:11]
	v_cvt_pk_f16_f32 v18, v60, v61
	v_cvt_pk_f16_f32 v19, v62, v63
	global_store_dwordx2 v2, v[18:19], s[12:13]
	s_add_u32 s12, s12, 0x100000
	s_addc_u32 s13, s13, 0
	s_add_u32 s20, s16, 0x18000
	s_addc_u32 s21, s17, 0
	global_load_dwordx4 v[8:11], v1, s[20:21]
	s_add_u32 s20, s20, 0x2000
	s_addc_u32 s21, s21, 0
	global_load_dwordx4 v[4:7], v1, s[20:21]
	s_lshl_b32 s22, s2, 13
	s_add_u32 s10, s6, s22
	s_addc_u32 s11, s7, 0
	s_lshl_b32 s22, s2, 12
	s_add_u32 s12, s18, 0x8000000
	s_addc_u32 s13, s19, 0
	s_add_u32 s12, s12, s22
	s_addc_u32 s13, s13, 0
	global_load_dwordx4 v[32:35], v1, s[10:11]
	s_add_u32 s10, s10, 0x200000
	s_addc_u32 s11, s11, 0
	global_load_dwordx4 v[36:39], v1, s[10:11]
	s_add_u32 s10, s10, 0x200000
	s_addc_u32 s11, s11, 0
	s_waitcnt vmcnt(0)
	v_pk_add_f32 v[4:5], v[4:5], 1.0 op_sel_hi:[1,0]
	v_pk_add_f32 v[6:7], v[6:7], 1.0 op_sel_hi:[1,0]
	v_pk_fma_f32 v[32:33], v[32:33], v[4:5], v[8:9]
	v_pk_fma_f32 v[34:35], v[34:35], v[6:7], v[10:11]
	v_cvt_pk_f16_f32 v12, v32, v33
	v_cvt_pk_f16_f32 v13, v34, v35
	global_store_dwordx2 v2, v[12:13], s[12:13]
	s_add_u32 s12, s12, 0x100000
	s_addc_u32 s13, s13, 0
	v_pk_fma_f32 v[36:37], v[36:37], v[4:5], v[8:9]
	v_pk_fma_f32 v[38:39], v[38:39], v[6:7], v[10:11]
	v_cvt_pk_f16_f32 v14, v36, v37
	v_cvt_pk_f16_f32 v15, v38, v39
	global_store_dwordx2 v2, v[14:15], s[12:13]
	s_add_u32 s12, s12, 0x100000
	s_addc_u32 s13, s13, 0
